# phase 0: start workgroup of each weight-conversion job rotated so the tiles of the five jobs spread evenly over the workgroups
# baseline (speedup 1.0000x reference)
.LBB0_3:
	s_or_b64 exec, exec, s[0:1]
	s_load_dword s0, s[92:93], 0xc0
	s_waitcnt lgkmcnt(0)
	s_barrier
	s_cmp_lg_u32 s0, 0
	s_cselect_b64 s[0:1], -1, 0
	s_and_b64 vcc, exec, s[0:1]
	s_cbranch_vccnz .LBB0_544
	s_load_dwordx2 s[22:23], s[92:93], 0x28
	s_load_dwordx8 s[8:15], s[92:93], 0x40
	s_load_dwordx2 s[20:21], s[92:93], 0x98
	s_load_dwordx4 s[16:19], s[92:93], 0x70
	v_lshlrev_b32_e32 v2, 1, v1
	v_and_b32_e32 v2, 0xfe, v2
	v_and_b32_e32 v18, 63, v1
	v_lshrrev_b32_e32 v19, 6, v1
	v_mul_u32_u24_e32 v12, 0x104, v2
	v_lshlrev_b32_e32 v2, 1, v2
	v_mov_b32_e32 v3, 0
	s_add_i32 s100, s2, 200
	s_sub_i32 s101, s100, s3
	s_cmp_ge_u32 s100, s3
	s_cselect_b32 s100, s101, s100
	s_cmp_lt_i32 s100, 32
	v_lshlrev_b32_e32 v4, 2, v18
	v_lshrrev_b32_e32 v20, 7, v1
	s_waitcnt lgkmcnt(0)
	v_lshl_add_u64 v[2:3], s[20:21], 0, v[2:3]
	v_mul_u32_u24_e32 v5, 0x104, v19
	s_mov_b64 s[4:5], 0x1700000
	s_cselect_b64 s[24:25], -1, 0
	s_add_i32 s100, s2, 232
	s_sub_i32 s101, s100, s3
	s_cmp_ge_u32 s100, s3
	s_cselect_b32 s100, s101, s100
	s_cmp_lt_i32 s100, 64
	v_add3_u32 v21, 0, v4, v5
	v_lshl_add_u64 v[4:5], v[2:3], 0, s[4:5]
	s_mov_b64 s[4:5], 0x1b00000
	v_lshlrev_b32_e32 v13, 1, v20
	s_cselect_b64 s[26:27], -1, 0
	s_add_i32 s100, s2, 40
	s_sub_i32 s101, s100, s3
	s_cmp_ge_u32 s100, s3
	s_cselect_b32 s100, s101, s100
	s_cmpk_lt_i32 s100, 0x160
	v_lshl_add_u64 v[6:7], v[2:3], 0, s[4:5]
	s_mov_b64 s[4:5], 0x2300000
	v_and_b32_e32 v22, 8, v13
	v_add_u32_e32 v24, 24, v13
	v_lshlrev_b32_e32 v13, 2, v20
	s_cselect_b64 s[28:29], -1, 0
	s_add_i32 s100, s2, 136
	s_sub_i32 s101, s100, s3
	s_cmp_ge_u32 s100, s3
	s_cselect_b32 s100, s101, s100
	s_cmpk_lt_i32 s100, 0xb0
	s_mov_b32 s37, 0
	v_lshl_add_u64 v[8:9], v[2:3], 0, s[4:5]
	s_mov_b64 s[4:5], 0x4f00000
	v_add_u32_e32 v14, 12, v20
	v_add3_u32 v25, v12, v13, 0
	v_add_u32_e32 v12, 4, v20
	s_cselect_b64 s[34:35], -1, 0
	v_lshl_add_u64 v[10:11], v[2:3], 0, s[4:5]
	v_lshrrev_b32_e32 v23, 1, v14
	v_lshrrev_b32_e32 v26, 1, v12
	s_mov_b32 s33, 0xb80000
	s_movk_i32 s52, 0x5ff
	s_movk_i32 s53, 0x8ff
	s_movk_i32 s54, 0xffc3
	s_movk_i32 s55, 0xaff
	s_movk_i32 s56, 0xb07
	s_movk_i32 s57, 0xb47
	s_movk_i32 s58, 0x400
	s_movk_i32 s59, 0x200
	s_movk_i32 s60, 0x1600
	s_movk_i32 s61, 0x5800
	v_mov_b32_e32 v27, 0xfffff500
	v_mov_b32_e32 v28, 0x80
	v_mov_b32_e32 v29, 0x580000
	s_mov_b32 s36, s37
	s_branch .LBB0_6

.LBB0_222:
	s_andn2_b64 vcc, exec, s[24:25]
	s_lshl_b64 s[6:7], s[36:37], 21
	s_cbranch_vccnz .LBB0_293
	s_add_u32 s38, s12, s6
	s_addc_u32 s39, s13, s7
	s_lshl_b64 s[4:5], s[36:37], 20
	v_lshl_add_u64 v[12:13], v[4:5], 0, s[4:5]
	s_add_i32 s44, s2, 200
	s_sub_i32 s101, s44, s3
	s_cmp_ge_u32 s44, s3
	s_cselect_b32 s44, s101, s44
	s_branch .LBB0_225

.LBB0_293:
	s_andn2_b64 vcc, exec, s[26:27]
	s_cbranch_vccnz .LBB0_364
	s_lshl_b64 s[4:5], s[36:37], 22
	s_add_u32 s38, s14, s4
	s_addc_u32 s39, s15, s5
	v_lshl_add_u64 v[12:13], v[6:7], 0, s[6:7]
	s_add_i32 s42, s2, 232
	s_sub_i32 s101, s42, s3
	s_cmp_ge_u32 s42, s3
	s_cselect_b32 s42, s101, s42
	s_branch .LBB0_296

.LBB0_364:
	s_mul_hi_u32 s5, s36, 0xb00000
	s_andn2_b64 vcc, exec, s[28:29]
	s_mul_i32 s4, s36, 0xb00000
	s_cbranch_vccnz .LBB0_441
	s_mul_i32 s6, s36, 0x1600000
	s_mul_hi_u32 s7, s36, 0x1600000
	s_add_u32 s6, s16, s6
	s_addc_u32 s7, s17, s7
	v_lshl_add_u64 v[12:13], v[8:9], 0, s[4:5]
	s_add_i32 s42, s2, 40
	s_sub_i32 s101, s42, s3
	s_cmp_ge_u32 s42, s3
	s_cselect_b32 s42, s101, s42
	s_branch .LBB0_367

.LBB0_441:
	s_andn2_b64 vcc, exec, s[34:35]
	s_cbranch_vccnz .LBB0_5
	s_add_u32 s6, s18, s4
	s_addc_u32 s7, s19, s5
	v_mad_u64_u32 v[12:13], s[4:5], s36, v29, v[10:11]
	s_add_i32 s42, s2, 136
	s_sub_i32 s101, s42, s3
	s_cmp_ge_u32 s42, s3
	s_cselect_b32 s42, s101, s42
	s_branch .LBB0_444
